# v33 with the static raise of waves 0-3 dropped during the scan phase (s_setprio 0 at its start, raise restored at its end): raise active in the GEMM/row phases only
# speedup vs baseline: 1.0036x; 1.0036x over previous
.LBB0_520:
	s_setprio 0
	v_readlane_b32 s4, v251, 30
	v_readlane_b32 s5, v251, 31
	s_xor_b64 s[4:5], s[4:5], -1
	v_writelane_b32 v253, s4, 34
	v_readlane_b32 s20, v252, 27
	v_readlane_b32 s21, v252, 28
	v_writelane_b32 v253, s5, 35
	v_readlane_b32 s4, v248, 3
	v_readlane_b32 s5, v248, 4
	s_mov_b64 s[8:9], s[4:5]
	s_cmp_le_i32 s8, s18
	v_readlane_b32 s6, v248, 5
	v_readlane_b32 s7, v248, 6
	s_cselect_b64 s[4:5], -1, 0
	s_cmp_lt_i32 s18, s9
	s_cselect_b64 s[6:7], -1, 0
	s_and_b64 s[22:23], s[4:5], s[6:7]
	v_readlane_b32 s4, v252, 15
	v_readlane_b32 s5, v252, 16
	s_mov_b32 s7, s5
	s_lshl_b32 s6, s20, 11
	v_writelane_b32 v252, s4, 15
	s_lshl_b64 s[24:25], s[6:7], 2
	s_nop 0
	v_writelane_b32 v252, s5, 16
	v_readlane_b32 s4, v248, 52
	v_readlane_b32 s12, v248, 60
	v_readlane_b32 s5, v248, 53
	v_readlane_b32 s13, v248, 61
	s_add_u32 s4, s12, s24
	v_writelane_b32 v253, s24, 36
	s_addc_u32 s5, s13, s25
	v_readlane_b32 s6, v248, 54
	v_writelane_b32 v253, s25, 37
	v_writelane_b32 v253, s4, 38
	v_readlane_b32 s7, v248, 55
	v_readlane_b32 s8, v248, 56
	v_writelane_b32 v253, s5, 39
	v_writelane_b32 v253, s22, 40
	s_lshl_b32 s4, s20, 25
	s_andn2_b64 vcc, exec, s[22:23]
	v_writelane_b32 v253, s23, 41
	v_writelane_b32 v253, s4, 42
	v_readlane_b32 s9, v248, 57
	v_readlane_b32 s10, v248, 58
	v_readlane_b32 s11, v248, 59
	v_readlane_b32 s14, v248, 62
	v_readlane_b32 s15, v248, 63
	v_readlane_b32 s16, v249, 0
	v_readlane_b32 s17, v249, 1
	v_readlane_b32 s18, v249, 2
	v_readlane_b32 s19, v249, 3
	s_cbranch_vccnz .LBB0_1506
	v_readlane_b32 s6, v248, 1
	v_readlane_b32 s7, v248, 2
	v_readlane_b32 s4, v251, 21
	v_readlane_b32 s5, v251, 22
	v_writelane_b32 v252, s6, 37
	s_andn2_b64 vcc, exec, s[4:5]
	s_nop 0
	v_writelane_b32 v252, s7, 38
	s_cbranch_vccnz .LBB0_619
	v_readlane_b32 s4, v250, 33
	v_readlane_b32 s5, v250, 34
	s_andn2_b64 vcc, exec, s[4:5]
	s_cbranch_vccnz .LBB0_595
	v_readlane_b32 s4, v252, 37
	v_readlane_b32 s5, v252, 38
	s_add_u32 s6, s4, 0x3cf00000
	v_writelane_b32 v252, s6, 35
	s_addc_u32 s6, s5, 0
	v_writelane_b32 v252, s6, 36
	s_add_u32 s6, s4, 0x3e000000
	v_writelane_b32 v252, s6, 39
	s_addc_u32 s6, s5, 0
	v_writelane_b32 v252, s6, 41
	s_add_u32 s6, s4, 0x4f900000
	s_addc_u32 s7, s5, 0
	v_writelane_b32 v253, s6, 43
	s_nop 1
	v_writelane_b32 v253, s7, 44
	s_add_u32 s6, s4, 0x7cd00000
	v_writelane_b32 v252, s6, 43
	s_addc_u32 s6, s5, 0
	v_writelane_b32 v252, s6, 44
	s_add_u32 s6, s4, 0x7de00000
	v_writelane_b32 v252, s6, 45
	s_addc_u32 s6, s5, 0
	v_writelane_b32 v252, s6, 46
	s_add_u32 s6, s4, 0x7ef00000
	s_addc_u32 s7, s5, 0
	v_writelane_b32 v252, s6, 47
	s_nop 1
	v_writelane_b32 v252, s7, 48
	s_add_u32 s6, s4, 0x80000000
	s_addc_u32 s7, s5, 0
	s_add_u32 s4, s4, 0x80100000
	s_addc_u32 s5, s5, 0
	v_writelane_b32 v251, s6, 30
	v_writelane_b32 v253, s4, 45
	s_lshl_b64 s[0:1], s[0:1], 2
	v_writelane_b32 v251, s7, 31
	v_writelane_b32 v253, s5, 46
	v_readlane_b32 s4, v248, 52
	v_readlane_b32 s8, v248, 56
	v_readlane_b32 s9, v248, 57
	s_add_u32 s0, s8, s0
	s_addc_u32 s1, s9, s1
	v_writelane_b32 v252, s0, 49
	v_readlane_b32 s10, v248, 58
	v_readlane_b32 s11, v248, 59
	v_writelane_b32 v252, s1, 50
	v_readlane_b32 s51, v251, 45
	v_readlane_b32 s0, v252, 29
	v_readlane_b32 s1, v252, 30
	s_lshl_b64 s[0:1], s[0:1], 2
	s_add_u32 s0, s10, s0
	s_addc_u32 s1, s11, s1
	v_writelane_b32 v252, s0, 51
	v_readlane_b32 s5, v248, 53
	v_readlane_b32 s6, v248, 54
	v_writelane_b32 v252, s1, 52
	v_readlane_b32 s0, v251, 44
	v_readlane_b32 s7, v248, 55
	v_readlane_b32 s12, v248, 60
	v_readlane_b32 s13, v248, 61
	v_readlane_b32 s14, v248, 62
	v_readlane_b32 s15, v248, 63
	v_readlane_b32 s16, v249, 0
	v_readlane_b32 s17, v249, 1
	v_readlane_b32 s18, v249, 2
	v_readlane_b32 s19, v249, 3
	s_branch .LBB0_525

.LBB0_1506:
	v_readfirstlane_b32 s98, v0
	s_nop 3
	s_and_b32 s98, s98, 0x3ff
	s_lshr_b32 s98, s98, 6
	s_cmp_lt_u32 s98, 4
	s_cbranch_scc0 .Lprio_done2
	s_setprio 1
